# PH2 sample S5 step: c_re/c_im and trailing loads issued with the first load batch (two memory round trips less per task)
# speedup vs baseline: 1.1179x; 1.0048x over previous
; __device__ __forceinline__ f32x2 cmul(f32x2 a, f32x2 b) { return (f32x2){a.x * b.x - a.y * b.y, a.x * b.y + a.y * b.x}; }
; __global__ void __launch_bounds__(512, 2) fwd_kernel(Args a) {
;     ...
;         for (int task = gw; task < NS * NG; task += NGW) {
;             const int ns = task >> 5, g = task & 31; const int gp = g * NP + lane;
;             const float* ur = USAMP + (size_t)ns * 512 + g * 16;
;             float uu[NH];
; #pragma unroll
;             for (int h = 0; h < NH; ++h) uu[h] = ur[h];
;             f32x2 bu = (f32x2){0.f, 0.f};
; #pragma unroll
;             for (int h = 0; h < NH; ++h) { const f32x2 bb = BBAR[(size_t)gp * NH + h]; bu.x += bb.x * uu[h]; bu.y += bb.y * uu[h]; }
;             const f32x2 h0 = (f32x2){st_re[(size_t)ns * 2048 + gp], st_im[(size_t)ns * 2048 + gp]};
;             const f32x2 hn = cmul(ABAR[gp], h0) + bu;
;             out[O_SRE + (size_t)ns * 2048 + gp] = hn.x; out[O_SIM + (size_t)ns * 2048 + gp] = hn.y;
;             float cr[NH], ci[NH];
; #pragma unroll
;             for (int h = 0; h < NH; ++h) { cr[h] = c_re[(size_t)(g * NH + h) * NP + lane]; ci[h] = c_im[(size_t)(g * NH + h) * NP + lane]; }
.LBB0_348:
	s_ashr_i32 s50, s57, 5
	s_and_b32 s58, s57, 31
	s_ashr_i32 s51, s50, 31
	s_lshl_b32 s48, s58, 6
	s_lshl_b64 s[54:55], s[50:51], 11
	s_add_u32 s52, s0, s54
	v_or_b32_e32 v63, s48, v154
	s_addc_u32 s53, s1, s55
	v_mov_b32_e32 v26, s48
	v_lshlrev_b32_e32 v58, 7, v63
	s_waitcnt lgkmcnt(0)
	global_load_dwordx4 v[14:17], v26, s[52:53] offset:48
	global_load_dwordx4 v[18:21], v26, s[52:53] offset:32
	global_load_dwordx4 v[22:25], v26, s[52:53] offset:16
	s_nop 0
	global_load_dwordx4 v[26:29], v26, s[52:53]
	s_nop 0
	global_load_dwordx4 v[30:33], v58, s[46:47] offset:16
	global_load_dwordx4 v[34:37], v58, s[46:47]
	v_or_b32_e32 v38, s54, v63
	v_mov_b32_e32 v39, s55
	v_lshlrev_b64 v[38:39], 2, v[38:39]
	v_lshl_add_u64 v[40:41], s[26:27], 0, v[38:39]
	global_load_dword v62, v[40:41], off
	v_lshlrev_b32_e32 v40, 3, v63
	v_lshl_add_u64 v[38:39], s[24:25], 0, v[38:39]
	global_load_dwordx2 v[64:65], v40, s[44:45]
	global_load_dword v66, v[38:39], off
	s_nop 0
	global_load_dwordx4 v[38:41], v58, s[46:47] offset:32
	global_load_dwordx4 v[42:45], v58, s[46:47] offset:48
	global_load_dwordx4 v[46:49], v58, s[46:47] offset:64
	global_load_dwordx4 v[50:53], v58, s[46:47] offset:80
	global_load_dwordx4 v[54:57], v58, s[46:47] offset:96
	s_nop 0
	global_load_dwordx4 v[58:61], v58, s[46:47] offset:112
	s_add_u32 s52, s52, s48
	s_addc_u32 s53, s53, 0
	s_lshl_b64 s[54:55], s[50:51], 13
	s_add_u32 s54, s20, s54
	v_lshlrev_b32_e32 v94, 2, v63
	s_addc_u32 s55, s21, s55
	v_lshl_add_u64 v[68:69], s[54:55], 0, v[94:95]
	v_add_co_u32_e32 v74, vcc, s6, v68
	s_lshl_b32 s48, s58, 12
	s_nop 0
	v_addc_co_u32_e32 v75, vcc, 0, v69, vcc
	v_add_co_u32_e32 v68, vcc, s7, v68
	v_lshl_add_u64 v[72:73], v[2:3], 0, s[48:49]
	s_nop 0
	v_addc_co_u32_e32 v69, vcc, 0, v69, vcc
	v_lshl_add_u64 v[70:71], v[0:1], 0, s[48:49]
	v_lshl_or_b32 v212, s58, 4, v4
	v_lshlrev_b32_e32 v212, 2, v212
	v_lshlrev_b32_e32 v213, 2, v4
	global_load_dword v212, v212, s[42:43]
	global_load_dword v213, v213, s[52:53]
	global_load_dword v180, v[72:73], off
	global_load_dword v181, v[72:73], off offset:256
	global_load_dword v182, v[72:73], off offset:512
	global_load_dword v183, v[72:73], off offset:768
	global_load_dword v184, v[72:73], off offset:1024
	global_load_dword v185, v[72:73], off offset:1280
	global_load_dword v186, v[72:73], off offset:1536
	global_load_dword v187, v[72:73], off offset:1792
	global_load_dword v188, v[72:73], off offset:2048
	global_load_dword v189, v[72:73], off offset:2304
	global_load_dword v190, v[72:73], off offset:2560
	global_load_dword v191, v[72:73], off offset:2816
	global_load_dword v192, v[72:73], off offset:3072
	global_load_dword v193, v[72:73], off offset:3328
	global_load_dword v194, v[72:73], off offset:3584
	global_load_dword v195, v[72:73], off offset:3840
	global_load_dword v196, v[70:71], off
	global_load_dword v197, v[70:71], off offset:256
	global_load_dword v198, v[70:71], off offset:512
	global_load_dword v199, v[70:71], off offset:768
	global_load_dword v200, v[70:71], off offset:1024
	global_load_dword v201, v[70:71], off offset:1280
	global_load_dword v202, v[70:71], off offset:1536
	global_load_dword v203, v[70:71], off offset:1792
	global_load_dword v204, v[70:71], off offset:2048
	global_load_dword v205, v[70:71], off offset:2304
	global_load_dword v206, v[70:71], off offset:2560
	global_load_dword v207, v[70:71], off offset:2816
	global_load_dword v208, v[70:71], off offset:3072
	global_load_dword v209, v[70:71], off offset:3328
	global_load_dword v210, v[70:71], off offset:3584
	global_load_dword v211, v[70:71], off offset:3840
	s_waitcnt vmcnt(48)
	v_mov_b32_e32 v82, v17
	s_waitcnt vmcnt(47)
	v_mov_b32_e32 v80, v21
	s_waitcnt vmcnt(46)
	v_mov_b32_e32 v78, v25
	s_waitcnt vmcnt(45)
	v_mov_b32_e32 v76, v29
	s_waitcnt vmcnt(43)
	v_pk_fma_f32 v[34:35], v[34:35], v[26:27], 0 op_sel_hi:[1,0,0]
	s_nop 0
	v_pk_fma_f32 v[26:27], v[36:37], v[26:27], v[34:35] op_sel:[0,1,0]
	s_waitcnt vmcnt(41)
	v_pk_mul_f32 v[34:35], v[62:63], v[64:65] op_sel:[0,1] op_sel_hi:[0,0]
	v_pk_fma_f32 v[26:27], v[30:31], v[28:29], v[26:27] op_sel_hi:[1,0,1]
	s_waitcnt vmcnt(40)
	v_pk_fma_f32 v[28:29], v[66:67], v[64:65], v[34:35] neg_lo:[0,0,1] neg_hi:[0,0,1]
	v_pk_fma_f32 v[26:27], v[32:33], v[76:77], v[26:27] op_sel_hi:[1,0,1]
	v_pk_fma_f32 v[30:31], v[66:67], v[64:65], v[34:35] op_sel_hi:[0,1,1]
	s_waitcnt vmcnt(39)
	v_pk_fma_f32 v[26:27], v[38:39], v[22:23], v[26:27] op_sel_hi:[1,0,1]
	v_mov_b32_e32 v29, v31
	v_pk_fma_f32 v[22:23], v[40:41], v[22:23], v[26:27] op_sel:[0,1,0]
	s_waitcnt vmcnt(38)
	v_pk_fma_f32 v[22:23], v[42:43], v[24:25], v[22:23] op_sel_hi:[1,0,1]
	s_nop 0
	v_pk_fma_f32 v[22:23], v[44:45], v[78:79], v[22:23] op_sel_hi:[1,0,1]
	s_waitcnt vmcnt(37)
	v_pk_fma_f32 v[22:23], v[46:47], v[18:19], v[22:23] op_sel_hi:[1,0,1]
	s_nop 0
	v_pk_fma_f32 v[18:19], v[48:49], v[18:19], v[22:23] op_sel:[0,1,0]
	s_waitcnt vmcnt(36)
	v_pk_fma_f32 v[18:19], v[50:51], v[20:21], v[18:19] op_sel_hi:[1,0,1]
	s_nop 0
	v_pk_fma_f32 v[18:19], v[52:53], v[80:81], v[18:19] op_sel_hi:[1,0,1]
	s_waitcnt vmcnt(35)
	v_pk_fma_f32 v[18:19], v[54:55], v[14:15], v[18:19] op_sel_hi:[1,0,1]
	s_nop 0
	v_pk_fma_f32 v[14:15], v[56:57], v[14:15], v[18:19] op_sel:[0,1,0]
	s_waitcnt vmcnt(34)
	v_pk_fma_f32 v[14:15], v[58:59], v[16:17], v[14:15] op_sel_hi:[1,0,1]
	s_nop 0
	v_pk_fma_f32 v[14:15], v[60:61], v[82:83], v[14:15] op_sel_hi:[1,0,1]
	s_nop 0
	v_pk_add_f32 v[14:15], v[14:15], v[28:29]
	global_store_dword v[74:75], v14, off
	global_store_dword v[68:69], v15, off
	s_waitcnt vmcnt(33)
; __device__ __forceinline__ unsigned cvt_pk_bf16(float lo, float hi) { unsigned r; asm volatile("v_cvt_pk_bf16_f32 %0, %1, %2" : "=v"(r) : "v"(lo), "v"(hi)); return r; }
; __device__ __forceinline__ float gelu_exact(float v) { return 0.5f * v * (1.0f + erff(v * 0.70710678118654752f)); }
; __global__ void __launch_bounds__(512, 2) fwd_kernel(Args a) {
;     ...
;             for (int h = 0; h < NH; ++h) { cr[h] = c_re[(size_t)(g * NH + h) * NP + lane]; ci[h] = c_im[(size_t)(g * NH + h) * NP + lane]; }
;             float t[NH];
; #pragma unroll
;             for (int h = 0; h < NH; ++h) t[h] = cr[h] * hn.x - ci[h] * hn.y;
;             const bool b5 = (lane & 32) != 0, b4 = (lane & 16) != 0, b3 = (lane & 8) != 0, b2 = (lane & 4) != 0;
;             float ra[8], rb[4], rc[2];
; #pragma unroll
;             for (int i = 0; i < 8; ++i) { const float keep = b5 ? t[i + 8] : t[i], send = b5 ? t[i] : t[i + 8]; ra[i] = keep + __shfl_xor(send, 32); }
; #pragma unroll
;             for (int i = 0; i < 4; ++i) { const float keep = b4 ? ra[i + 4] : ra[i], send = b4 ? ra[i] : ra[i + 4]; rb[i] = keep + __shfl_xor(send, 16); }
; #pragma unroll
;             for (int i = 0; i < 2; ++i) { const float keep = b3 ? rb[i + 2] : rb[i], send = b3 ? rb[i] : rb[i + 2]; rc[i] = keep + __shfl_xor(send, 8); }
;             float rd; { const float keep = b2 ? rc[1] : rc[0], send = b2 ? rc[0] : rc[1]; rd = keep + __shfl_xor(send, 4); }
;             rd += __shfl_xor(rd, 2); rd += __shfl_xor(rd, 1);
;             const int hsel = (b5 ? 8 : 0) + (b4 ? 4 : 0) + (b3 ? 2 : 0) + (b2 ? 1 : 0);
;             const float my = rd + s5_d[g * NH + hsel] * ur[hsel];
;             if ((lane & 3) == 0) YG[(size_t)(MP + ns) * 512 + g * 16 + hsel] = (bf16)(cvt_pk_bf16(gelu_exact(my), 0.f) & 0xffffu);
	v_mul_f32_e32 v16, v15, v180
	s_waitcnt vmcnt(32)
	v_mul_f32_e32 v17, v15, v181
	s_waitcnt vmcnt(31)
	v_mul_f32_e32 v18, v15, v182
	s_waitcnt vmcnt(30)
	v_mul_f32_e32 v19, v15, v183
	s_waitcnt vmcnt(29)
	v_mul_f32_e32 v20, v15, v184
	s_waitcnt vmcnt(28)
	v_mul_f32_e32 v21, v15, v185
	s_waitcnt vmcnt(27)
	v_mul_f32_e32 v22, v15, v186
	s_waitcnt vmcnt(26)
	v_mul_f32_e32 v23, v15, v187
	s_waitcnt vmcnt(25)
	v_mul_f32_e32 v24, v15, v188
	s_waitcnt vmcnt(24)
	v_mul_f32_e32 v25, v15, v189
	s_waitcnt vmcnt(23)
	v_mul_f32_e32 v26, v15, v190
	s_waitcnt vmcnt(22)
	v_mul_f32_e32 v27, v15, v191
	s_waitcnt vmcnt(21)
	v_mul_f32_e32 v28, v15, v192
	s_waitcnt vmcnt(20)
	v_mul_f32_e32 v29, v15, v193
	s_waitcnt vmcnt(19)
	v_mul_f32_e32 v30, v15, v194
	s_waitcnt vmcnt(18)
	v_mul_f32_e32 v15, v15, v195
	s_waitcnt vmcnt(17)
	v_fma_f32 v16, v14, v196, -v16
	s_waitcnt vmcnt(16)
	v_fma_f32 v17, v14, v197, -v17
	s_waitcnt vmcnt(15)
	v_fma_f32 v18, v14, v198, -v18
	s_waitcnt vmcnt(14)
	v_fma_f32 v19, v14, v199, -v19
	s_waitcnt vmcnt(13)
	v_fma_f32 v20, v14, v200, -v20
	s_waitcnt vmcnt(12)
	v_fma_f32 v21, v14, v201, -v21
	s_waitcnt vmcnt(11)
	v_fma_f32 v22, v14, v202, -v22
	s_waitcnt vmcnt(10)
	v_fma_f32 v23, v14, v203, -v23
	s_waitcnt vmcnt(9)
	v_fma_f32 v24, v14, v204, -v24
	s_waitcnt vmcnt(8)
	v_fma_f32 v25, v14, v205, -v25
	s_waitcnt vmcnt(7)
	v_fma_f32 v26, v14, v206, -v26
	s_waitcnt vmcnt(6)
	v_fma_f32 v27, v14, v207, -v27
	s_waitcnt vmcnt(5)
	v_fma_f32 v28, v14, v208, -v28
	s_waitcnt vmcnt(4)
	v_fma_f32 v29, v14, v209, -v29
	s_waitcnt vmcnt(3)
	v_fma_f32 v30, v14, v210, -v30
	s_waitcnt vmcnt(2)
	v_fma_f32 v14, v14, v211, -v15
	v_cndmask_b32_e64 v15, v24, v16, s[8:9]
	v_cndmask_b32_e64 v16, v16, v24, s[8:9]
	v_cndmask_b32_e64 v24, v25, v17, s[8:9]
	v_cndmask_b32_e64 v17, v17, v25, s[8:9]
	v_cndmask_b32_e64 v25, v26, v18, s[8:9]
	v_cndmask_b32_e64 v18, v18, v26, s[8:9]
	v_cndmask_b32_e64 v26, v27, v19, s[8:9]
	v_cndmask_b32_e64 v19, v19, v27, s[8:9]
	v_cndmask_b32_e64 v27, v28, v20, s[8:9]
	v_cndmask_b32_e64 v20, v20, v28, s[8:9]
	v_cndmask_b32_e64 v28, v29, v21, s[8:9]
	v_cndmask_b32_e64 v21, v21, v29, s[8:9]
	v_cndmask_b32_e64 v29, v30, v22, s[8:9]
	v_cndmask_b32_e64 v22, v22, v30, s[8:9]
	v_cndmask_b32_e64 v30, v14, v23, s[8:9]
	v_cndmask_b32_e64 v14, v23, v14, s[8:9]
	ds_bpermute_b32 v16, v5, v16
	ds_bpermute_b32 v17, v5, v17
	ds_bpermute_b32 v18, v5, v18
	ds_bpermute_b32 v19, v5, v19
	ds_bpermute_b32 v20, v5, v20
	ds_bpermute_b32 v21, v5, v21
	ds_bpermute_b32 v22, v5, v22
	ds_bpermute_b32 v14, v5, v14
	s_waitcnt lgkmcnt(7)
	v_add_f32_e32 v15, v15, v16
	s_waitcnt lgkmcnt(6)
	v_add_f32_e32 v16, v24, v17
	s_waitcnt lgkmcnt(5)
	v_add_f32_e32 v17, v25, v18
	s_waitcnt lgkmcnt(4)
	v_add_f32_e32 v18, v26, v19
	s_waitcnt lgkmcnt(3)
	v_add_f32_e32 v19, v27, v20
	s_waitcnt lgkmcnt(2)
	v_add_f32_e32 v20, v28, v21
	s_waitcnt lgkmcnt(1)
	v_add_f32_e32 v21, v29, v22
	s_waitcnt lgkmcnt(0)
	v_add_f32_e32 v14, v30, v14
	v_cndmask_b32_e64 v22, v19, v15, s[10:11]
	v_cndmask_b32_e64 v15, v15, v19, s[10:11]
	v_cndmask_b32_e64 v19, v20, v16, s[10:11]
	v_cndmask_b32_e64 v16, v16, v20, s[10:11]
	v_cndmask_b32_e64 v20, v21, v17, s[10:11]
	v_cndmask_b32_e64 v17, v17, v21, s[10:11]
	v_cndmask_b32_e64 v21, v18, v14, s[10:11]
	ds_bpermute_b32 v15, v6, v15
	ds_bpermute_b32 v16, v6, v16
	ds_bpermute_b32 v17, v6, v17
	ds_bpermute_b32 v21, v6, v21
	v_cndmask_b32_e64 v14, v14, v18, s[10:11]
	s_waitcnt lgkmcnt(3)
	v_add_f32_e32 v15, v22, v15
	s_waitcnt lgkmcnt(2)
	v_add_f32_e32 v16, v19, v16
	s_waitcnt lgkmcnt(1)
	v_add_f32_e32 v17, v20, v17
	s_waitcnt lgkmcnt(0)
	v_add_f32_e32 v14, v14, v21
	v_cndmask_b32_e64 v18, v15, v17, s[12:13]
	v_cndmask_b32_e64 v19, v16, v14, s[12:13]
	ds_bpermute_b32 v18, v7, v18
	ds_bpermute_b32 v19, v7, v19
	v_cndmask_b32_e64 v15, v17, v15, s[12:13]
	v_cndmask_b32_e64 v14, v14, v16, s[12:13]
	s_waitcnt lgkmcnt(1)
	v_add_f32_e32 v15, v15, v18
	s_waitcnt lgkmcnt(0)
	v_add_f32_e32 v14, v14, v19
	v_cndmask_b32_e64 v16, v15, v14, s[14:15]
	ds_bpermute_b32 v16, v8, v16
	v_cndmask_b32_e64 v14, v14, v15, s[14:15]
	s_waitcnt lgkmcnt(0)
	v_add_f32_e32 v14, v14, v16
	ds_bpermute_b32 v15, v9, v14
	s_waitcnt lgkmcnt(0)
	v_add_f32_e32 v14, v14, v15
	ds_bpermute_b32 v15, v10, v14
	s_and_saveexec_b64 s[54:55], s[16:17]
	s_cbranch_execz .LBB0_347
	s_lshl_b32 s48, s58, 4
	v_or_b32_e32 v16, s48, v4
	v_lshlrev_b32_e32 v16, 2, v16
	v_lshlrev_b32_e32 v17, 2, v4
	s_waitcnt lgkmcnt(0)
	v_add_f32_e32 v14, v14, v15
	v_fmac_f32_e32 v14, v212, v213
	v_mul_f32_e32 v15, 0x3f3504f3, v14
	v_cmp_nlt_f32_e64 s[52:53], |v15|, 1.0
	s_and_saveexec_b64 s[58:59], s[52:53]
	s_xor_b64 s[52:53], exec, s[58:59]
	s_cbranch_execz .LBB0_351
	v_fma_f32 v16, |v15|, s29, v12
	v_fma_f32 v16, |v15|, v16, s31
	v_fma_f32 v16, |v15|, v16, s33
	v_fma_f32 v16, |v15|, v16, s34
	v_fma_f32 v16, |v15|, v16, s35
	v_fma_f32 v16, |v15|, v16, s36
	v_fma_f32 v16, |v15|, v16, |v15|
	v_mul_f32_e32 v17, 0xbfb8aa3b, v16
	v_fma_f32 v18, v16, s37, -v17
	v_rndne_f32_e32 v19, v17
	v_fmac_f32_e32 v18, 0xb2a5705f, v16
	v_sub_f32_e32 v17, v17, v19
	v_add_f32_e32 v17, v17, v18
	v_cvt_i32_f32_e32 v18, v19
	v_exp_f32_e32 v17, v17
	v_cmp_nlt_f32_e32 vcc, s38, v16
	v_ldexp_f32 v17, v17, v18
	s_nop 0
	v_cndmask_b32_e32 v17, 0, v17, vcc
	v_cmp_ngt_f32_e32 vcc, s39, v16
	s_nop 1
	v_cndmask_b32_e32 v16, v13, v17, vcc
	v_sub_f32_e32 v16, 1.0, v16
